# dense sparse-attention loop: row-sum adds and second-half mask build moved into MFMA shadows (pure reorder)
# speedup vs baseline: 1.0060x; 1.0020x over previous
; #define B_WRITE(st) do { _Pragma("unroll") for (int i = 0; i < 2; ++i) { *(LAS u32x4*)(lds + (st) * A_STG + (srow_ + 32 * i) * A_KROW + sch * 16) = kreg[i]; \
;             *(LAS u32x4*)(lds + (st) * A_STG + A_KBUF + (srow_ + 32 * i) * A_VROW + sch * 16) = vreg[i]; } } while (0)
; __device__ __forceinline__ void phaseB(const Params& p, LAS unsigned char* lds, int wv) {
;     ...
;                 l0 += sacc0; l1 += sacc1;
;                 if (t + 1 < NT) B_WRITE((t + 1) & 1);
;                 __syncthreads();
.LBB0_736:
	s_add_u32 s0, s0, 0x4000
	s_addc_u32 s1, s1, 0
	s_add_i32 s16, s16, 64
	v_pk_add_f32 v[212:213], v[212:213], v[64:65]
	s_cmp_eq_u32 s11, s0
	v_add_u32_e32 v242, 8, v242
	s_waitcnt lgkmcnt(0)
	s_barrier
	s_cbranch_scc1 .LBB0_749

; __device__ __forceinline__ void phaseB(const Params& p, LAS unsigned char* lds, int wv) {
;     ...
;                 for (int hf = 0; hf < 2; ++hf) {
;                     f32x16 s0, s1;
; #pragma unroll
;                     for (int r = 0; r < 16; ++r) { const float cm = ((selm >> (16 * hf + r)) & 1u) ? 0.f : -1e30f; s0[r] = cm; s1[r] = cm; }
;                     const LAS unsigned char* kp = Kb + (32 * hf + pi32(r32)) * A_KROW + g * 128 + hi * 16;
; #pragma unroll
;                     for (int ds = 0; ds < 4; ++ds) { const bf16x8 kf = *(const LAS bf16x8*)(kp + 32 * ds);
;                         s0 = __builtin_amdgcn_mfma_f32_32x32x16_bf16(kf, qf2[0][ds], s0, 0, 0, 0); s1 = __builtin_amdgcn_mfma_f32_32x32x16_bf16(kf, qf2[1][ds], s1, 0, 0, 0); }
;                     if (!near) {
; #pragma unroll
;                         for (int r = 0; r < 16; ++r) { s0[r] = __builtin_amdgcn_exp2f(s0[r]); s1[r] = __builtin_amdgcn_exp2f(s1[r]); }
;                     } else {
;                         int ib = 223 - (qpos - k0 - 8 * hi - 32 * hf); asm volatile("" : "+v"(ib));
;                         const LAS float* tp0 = Tb + (2 * hp) * 320 + ib; const LAS float* tp1 = tp0 + 320;
; #pragma unroll
;                         for (int r = 0; r < 16; ++r) { s0[r] = __builtin_amdgcn_exp2f(s0[r] + tp0[16 * (r >> 3) + (r & 7)]); s1[r] = __builtin_amdgcn_exp2f(s1[r] + tp1[16 * (r >> 3) + (r & 7)]); }
;                     }
; #pragma unroll
;                     for (int r = 0; r < 16; ++r) { sacc0 += s0[r]; sacc1 += s1[r]; }
; #pragma unroll
;                     for (int jj = 0; jj < 2; ++jj) {
;                         const int j = 2 * hf + jj, rb = 8 * jj;
;                         u32x4 pw0, pw1;
;                         pw0.x = cvt_pk_bf16(s0[rb], s0[rb + 1]); pw0.y = cvt_pk_bf16(s0[rb + 2], s0[rb + 3]); pw0.z = cvt_pk_bf16(s0[rb + 4], s0[rb + 5]); pw0.w = cvt_pk_bf16(s0[rb + 6], s0[rb + 7]);
;                         pw1.x = cvt_pk_bf16(s1[rb], s1[rb + 1]); pw1.y = cvt_pk_bf16(s1[rb + 2], s1[rb + 3]); pw1.z = cvt_pk_bf16(s1[rb + 4], s1[rb + 5]); pw1.w = cvt_pk_bf16(s1[rb + 6], s1[rb + 7]);
;                         const bf16x8 pa0 = __builtin_bit_cast(bf16x8, pw0), pa1 = __builtin_bit_cast(bf16x8, pw1);
;                         const LAS unsigned char* vp = Vb + (16 * j + 8 * hi + ((lane & 15) >> 2)) * A_VROW + (g * 64 + 16 * ((lane >> 4) & 1) + 4 * (lane & 3)) * 2;
.LBB0_743:
	v_add_u32_e32 v95, s17, v241
	v_add_u32_e32 v245, v95, v240
	v_cvt_pk_bf16_f32 v96, v64, v65
	v_cvt_pk_bf16_f32 v97, v66, v67
	v_cvt_pk_bf16_f32 v98, v68, v69
	v_cvt_pk_bf16_f32 v99, v70, v71
	v_cvt_pk_bf16_f32 v100, v80, v81
	v_cvt_pk_bf16_f32 v101, v82, v83
	v_cvt_pk_bf16_f32 v102, v84, v85
	v_cvt_pk_bf16_f32 v103, v86, v87
	s_nop 6
	ds_read_b64_tr_b16 v[104:105], v245 offset:17408
	ds_read_b64_tr_b16 v[106:107], v245 offset:18688
	ds_read_b64_tr_b16 v[114:115], v245 offset:18752
	ds_read_b64_tr_b16 v[112:113], v245 offset:17472
	s_waitcnt lgkmcnt(2)
	v_mfma_f32_32x32x16_bf16 v[48:63], v[96:99], v[104:107], v[48:63]
	v_exp_f32_e32 v244, v111
	v_lshrrev_b32_e32 v95, v235, v129
	v_mfma_f32_32x32x16_bf16 v[16:31], v[100:103], v[104:107], v[16:31]
	v_bfe_i32 v144, v95, 0, 1
	v_bfe_i32 v145, v95, 1, 1
	v_bfe_i32 v146, v95, 2, 1
	v_bfe_i32 v147, v95, 3, 1
	v_bfe_i32 v148, v95, 4, 1
	v_bfe_i32 v149, v95, 5, 1
	s_waitcnt lgkmcnt(0)
	v_mfma_f32_32x32x16_bf16 v[32:47], v[96:99], v[112:115], v[32:47]
	v_bfe_i32 v150, v95, 6, 1
	v_bfe_i32 v151, v95, 7, 1
	v_cvt_pk_bf16_f32 v96, v72, v73
	v_cvt_pk_bf16_f32 v97, v74, v75
	v_cvt_pk_bf16_f32 v98, v76, v77
	v_cvt_pk_bf16_f32 v99, v78, v79
	v_mfma_f32_32x32x16_bf16 v[0:15], v[100:103], v[112:115], v[0:15]
	v_bfe_i32 v152, v95, 16, 1
	v_bfe_i32 v153, v95, 17, 1
	v_cvt_pk_bf16_f32 v100, v88, v89
	v_cvt_pk_bf16_f32 v101, v90, v91
	v_cvt_pk_bf16_f32 v102, v92, v93
	v_cvt_pk_bf16_f32 v103, v94, v244
	ds_read_b64_tr_b16 v[104:105], v245 offset:22528
	ds_read_b64_tr_b16 v[106:107], v245 offset:23808
	ds_read_b64_tr_b16 v[110:111], v245 offset:23872
	ds_read_b64_tr_b16 v[108:109], v245 offset:22592
	s_waitcnt lgkmcnt(2)
	v_mfma_f32_32x32x16_bf16 v[48:63], v[96:99], v[104:107], v[48:63]
	v_bfe_i32 v154, v95, 18, 1
	v_bfe_i32 v155, v95, 19, 1
	v_bfe_i32 v156, v95, 20, 1
	v_bfe_i32 v157, v95, 21, 1
	v_bfe_i32 v158, v95, 22, 1
	v_bfe_i32 v159, v95, 23, 1
	v_mfma_f32_32x32x16_bf16 v[16:31], v[100:103], v[104:107], v[16:31]
	v_bfi_b32 v144, v144, 0, v231
	v_bfi_b32 v145, v145, 0, v231
	v_bfi_b32 v146, v146, 0, v231
	v_bfi_b32 v147, v147, 0, v231
	v_bfi_b32 v148, v148, 0, v231
	v_bfi_b32 v149, v149, 0, v231
	s_waitcnt lgkmcnt(0)
	v_mfma_f32_32x32x16_bf16 v[32:47], v[96:99], v[108:111], v[32:47]
	v_bfi_b32 v150, v150, 0, v231
	v_bfi_b32 v151, v151, 0, v231
	v_bfi_b32 v152, v152, 0, v231
	v_bfi_b32 v153, v153, 0, v231
	v_bfi_b32 v154, v154, 0, v231
	v_bfi_b32 v155, v155, 0, v231
	v_mfma_f32_32x32x16_bf16 v[0:15], v[100:103], v[108:111], v[0:15]
	v_bfi_b32 v156, v156, 0, v231
	v_bfi_b32 v157, v157, 0, v231
	v_bfi_b32 v158, v158, 0, v231
	v_bfi_b32 v159, v159, 0, v231
	ds_read_b128 v[112:115], v128 offset:8704
	ds_read_b128 v[116:119], v128 offset:8736
	s_andn2_b64 vcc, exec, s[4:5]
	s_mov_b64 s[4:5], -1
	s_waitcnt lgkmcnt(1)
	v_mfma_f32_32x32x16_bf16 v[96:111], v[112:115], v[192:195], v[144:159]
	v_add_f32_e32 v64, 0, v64
	v_add_f32_e32 v80, 0, v80
	v_add_f32_e32 v64, v65, v64
	v_add_f32_e32 v65, v81, v80
	v_mfma_f32_32x32x16_bf16 v[144:159], v[112:115], v[176:179], v[144:159]
	v_add_f32_e32 v64, v66, v64
	v_add_f32_e32 v65, v82, v65
	v_add_f32_e32 v64, v67, v64
	v_add_f32_e32 v65, v83, v65
	s_waitcnt lgkmcnt(0)
	v_mfma_f32_32x32x16_bf16 v[144:159], v[116:119], v[180:183], v[144:159]
	v_add_f32_e32 v64, v68, v64
	v_add_f32_e32 v65, v84, v65
	v_add_f32_e32 v64, v69, v64
	v_add_f32_e32 v65, v85, v65
	v_mfma_f32_32x32x16_bf16 v[96:111], v[116:119], v[196:199], v[96:111]
	v_add_f32_e32 v64, v70, v64
	v_add_f32_e32 v65, v86, v65
	v_add_f32_e32 v64, v71, v64
	v_add_f32_e32 v65, v87, v65
	ds_read_b128 v[112:115], v128 offset:8768
	ds_read_b128 v[116:119], v128 offset:8800
	s_waitcnt lgkmcnt(1)
	v_mfma_f32_32x32x16_bf16 v[144:159], v[112:115], v[184:187], v[144:159]
	v_add_f32_e32 v64, v72, v64
	v_add_f32_e32 v65, v88, v65
	v_add_f32_e32 v64, v73, v64
	v_add_f32_e32 v65, v89, v65
	v_mfma_f32_32x32x16_bf16 v[96:111], v[112:115], v[200:203], v[96:111]
	v_add_f32_e32 v64, v74, v64
	v_add_f32_e32 v65, v90, v65
	v_add_f32_e32 v64, v75, v64
	v_add_f32_e32 v65, v91, v65
	s_waitcnt lgkmcnt(0)
	v_mfma_f32_32x32x16_bf16 v[144:159], v[116:119], v[188:191], v[144:159]
	v_add_f32_e32 v64, v76, v64
	v_add_f32_e32 v65, v92, v65
	v_add_f32_e32 v64, v77, v64
	v_add_f32_e32 v65, v93, v65
	v_mfma_f32_32x32x16_bf16 v[96:111], v[116:119], v[204:207], v[96:111]
	v_add_f32_e32 v64, v78, v64
	v_add_f32_e32 v65, v94, v65
	v_add_f32_e32 v64, v79, v64
	v_add_f32_e32 v65, v244, v65
	s_cbranch_vccnz .LBB0_745
	s_nop 9
	v_exp_f32_e32 v112, v144
	v_exp_f32_e32 v128, v96
	v_exp_f32_e32 v113, v145
	v_exp_f32_e32 v129, v97
	v_exp_f32_e32 v114, v146
	v_exp_f32_e32 v130, v98
	v_exp_f32_e32 v115, v147
	v_exp_f32_e32 v131, v99
	v_exp_f32_e32 v116, v148
	v_exp_f32_e32 v132, v100
	v_exp_f32_e32 v117, v149
	v_exp_f32_e32 v133, v101
	v_exp_f32_e32 v118, v150
	v_exp_f32_e32 v134, v102
	v_exp_f32_e32 v119, v151
	v_exp_f32_e32 v135, v103
	v_exp_f32_e32 v120, v152
	v_exp_f32_e32 v136, v104
	v_exp_f32_e32 v121, v153
	v_exp_f32_e32 v137, v105
	v_exp_f32_e32 v122, v154
	v_exp_f32_e32 v138, v106
	v_exp_f32_e32 v123, v155
	v_exp_f32_e32 v139, v107
	v_exp_f32_e32 v124, v156
	v_exp_f32_e32 v140, v108
	v_exp_f32_e32 v125, v157
	v_exp_f32_e32 v141, v109
	v_exp_f32_e32 v126, v158
	v_exp_f32_e32 v142, v110
	v_exp_f32_e32 v127, v159
	s_mov_b64 s[4:5], 0

; __device__ __forceinline__ unsigned cvt_pk_bf16(float lo, float hi) { unsigned r; asm volatile("v_cvt_pk_bf16_f32 %0, %1, %2" : "=v"(r) : "v"(lo), "v"(hi)); return r; }
; #define LAS __attribute__((address_space(3)))
; #define B_WRITE(st) do { _Pragma("unroll") for (int i = 0; i < 2; ++i) { *(LAS u32x4*)(lds + (st) * A_STG + (srow_ + 32 * i) * A_KROW + sch * 16) = kreg[i]; \
;             *(LAS u32x4*)(lds + (st) * A_STG + A_KBUF + (srow_ + 32 * i) * A_VROW + sch * 16) = vreg[i]; } } while (0)
; __device__ __forceinline__ void phaseB(const Params& p, LAS unsigned char* lds, int wv) {
;     ...
;                     for (int r = 0; r < 16; ++r) { sacc0 += s0[r]; sacc1 += s1[r]; }
; #pragma unroll
;                     for (int jj = 0; jj < 2; ++jj) {
;                         const int j = 2 * hf + jj, rb = 8 * jj;
;                         u32x4 pw0, pw1;
;                         pw0.x = cvt_pk_bf16(s0[rb], s0[rb + 1]); pw0.y = cvt_pk_bf16(s0[rb + 2], s0[rb + 3]); pw0.z = cvt_pk_bf16(s0[rb + 4], s0[rb + 5]); pw0.w = cvt_pk_bf16(s0[rb + 6], s0[rb + 7]);
;                         pw1.x = cvt_pk_bf16(s1[rb], s1[rb + 1]); pw1.y = cvt_pk_bf16(s1[rb + 2], s1[rb + 3]); pw1.z = cvt_pk_bf16(s1[rb + 4], s1[rb + 5]); pw1.w = cvt_pk_bf16(s1[rb + 6], s1[rb + 7]);
;                         const bf16x8 pa0 = __builtin_bit_cast(bf16x8, pw0), pa1 = __builtin_bit_cast(bf16x8, pw1);
;                         const LAS unsigned char* vp = Vb + (16 * j + 8 * hi + ((lane & 15) >> 2)) * A_VROW + (g * 64 + 16 * ((lane >> 4) & 1) + 4 * (lane & 3)) * 2;
; #pragma unroll
;                         for (int db = 0; db < 2; ++db) {
;                             const s16x4 lo = vtr(vp + db * 64), hv = vtr(vp + 4 * A_VROW + db * 64);
;                             const bf16x8 vf = (bf16x8){lo[0], lo[1], lo[2], lo[3], hv[0], hv[1], hv[2], hv[3]};
;                             O[0][db] = __builtin_amdgcn_mfma_f32_32x32x16_bf16(pa0, vf, O[0][db], 0, 0, 0);
;                             O[1][db] = __builtin_amdgcn_mfma_f32_32x32x16_bf16(pa1, vf, O[1][db], 0, 0, 0);
;                         }
;                     }
;                     __builtin_amdgcn_sched_barrier(0);
;                 }
;                 l0 += sacc0; l1 += sacc1;
;                 if (t + 1 < NT) B_WRITE((t + 1) & 1);
.LBB0_747:
	v_cvt_pk_bf16_f32 v96, v112, v113
	v_cvt_pk_bf16_f32 v97, v114, v115
	v_cvt_pk_bf16_f32 v98, v116, v117
	v_cvt_pk_bf16_f32 v99, v118, v119
	v_cvt_pk_bf16_f32 v100, v128, v129
	v_cvt_pk_bf16_f32 v101, v130, v131
	v_cvt_pk_bf16_f32 v102, v132, v133
	v_cvt_pk_bf16_f32 v103, v134, v135
	s_nop 8
	ds_read_b64_tr_b16 v[104:105], v245 offset:27648
	ds_read_b64_tr_b16 v[106:107], v245 offset:28928
	ds_read_b64_tr_b16 v[146:147], v245 offset:28992
	ds_read_b64_tr_b16 v[144:145], v245 offset:27712
	s_waitcnt lgkmcnt(2)
	v_mfma_f32_32x32x16_bf16 v[48:63], v[96:99], v[104:107], v[48:63]
	v_add_f32_e32 v64, v64, v112
	v_add_f32_e32 v65, v65, v128
	v_add_f32_e32 v64, v64, v113
	v_add_f32_e32 v65, v65, v129
	v_exp_f32_e32 v95, v111
	s_add_i32 s15, s15, 1
	v_mfma_f32_32x32x16_bf16 v[16:31], v[100:103], v[104:107], v[16:31]
	v_add_f32_e32 v64, v64, v114
	v_add_f32_e32 v65, v65, v130
	v_add_f32_e32 v64, v64, v115
	v_add_f32_e32 v65, v65, v131
	s_waitcnt lgkmcnt(0)
	v_mfma_f32_32x32x16_bf16 v[32:47], v[96:99], v[144:147], v[32:47]
	v_add_f32_e32 v64, v64, v116
	v_add_f32_e32 v65, v65, v132
	v_add_f32_e32 v64, v64, v117
	v_add_f32_e32 v65, v65, v133
	v_cvt_pk_bf16_f32 v96, v120, v121
	v_cvt_pk_bf16_f32 v97, v122, v123
	v_cvt_pk_bf16_f32 v98, v124, v125
	v_cvt_pk_bf16_f32 v99, v126, v127
	v_mfma_f32_32x32x16_bf16 v[0:15], v[100:103], v[144:147], v[0:15]
	v_add_f32_e32 v64, v64, v118
	v_add_f32_e32 v65, v65, v134
	v_add_f32_e32 v64, v64, v119
	v_add_f32_e32 v65, v65, v135
	v_cvt_pk_bf16_f32 v100, v136, v137
	v_cvt_pk_bf16_f32 v101, v138, v139
	v_cvt_pk_bf16_f32 v102, v140, v141
	v_cvt_pk_bf16_f32 v103, v142, v95
	ds_read_b64_tr_b16 v[104:105], v245 offset:32768
	ds_read_b64_tr_b16 v[106:107], v245 offset:34048
	ds_read_b64_tr_b16 v[110:111], v245 offset:34112
	ds_read_b64_tr_b16 v[108:109], v245 offset:32832
	s_waitcnt lgkmcnt(2)
	v_mfma_f32_32x32x16_bf16 v[48:63], v[96:99], v[104:107], v[48:63]
	v_add_f32_e32 v64, v64, v120
	v_add_f32_e32 v65, v65, v136
	v_add_f32_e32 v64, v64, v121
	v_add_f32_e32 v65, v65, v137
	v_mfma_f32_32x32x16_bf16 v[16:31], v[100:103], v[104:107], v[16:31]
	v_add_f32_e32 v64, v64, v122
	v_add_f32_e32 v65, v65, v138
	v_add_f32_e32 v64, v64, v123
	v_add_f32_e32 v65, v65, v139
	s_waitcnt lgkmcnt(0)
	v_mfma_f32_32x32x16_bf16 v[32:47], v[96:99], v[108:111], v[32:47]
	v_add_f32_e32 v64, v64, v124
	v_add_f32_e32 v65, v65, v140
	v_add_f32_e32 v64, v64, v125
	v_add_f32_e32 v65, v65, v141
	v_mfma_f32_32x32x16_bf16 v[0:15], v[100:103], v[108:111], v[0:15]
	v_add_f32_e32 v64, v64, v126
	v_add_f32_e32 v65, v65, v142
	v_add_f32_e32 v64, v64, v127
	v_add_f32_e32 v65, v65, v95
	s_and_b64 vcc, exec, s[2:3]
	s_cbranch_vccz .LBB0_736
	s_bitcmp1_b32 s15, 0
	s_cselect_b32 s2, 0x9400, 0
	v_add_u32_e32 v96, s2, v236
	v_add_u32_e32 v97, v96, v238
	v_add_u32_e32 v96, v96, v237
	ds_write_b128 v96, v[160:163]
	ds_write_b128 v97, v[164:167] offset:17408
	ds_write_b128 v96, v[168:171] offset:8704
	ds_write_b128 v97, v[172:175] offset:27648
	s_branch .LBB0_736
